# GQA loop: pointer/counter increments deferred from before the loop barrier to after the first K-fragment reads (hidden under LDS latency)
# speedup vs baseline: 1.0072x; 1.0072x over previous
; #define LAS __attribute__((address_space(3)))
; #define WAIT_BAR() asm volatile("s_waitcnt vmcnt(0) lgkmcnt(0)\n\ts_barrier" ::: "memory")
; #define WAIT_BAR() asm volatile("s_waitcnt vmcnt(0) lgkmcnt(0)\n\ts_barrier" ::: "memory")
; template <int NCB, bool DIFF, bool STAT>
; __device__ __forceinline__ void attn_unit(LAS char* lds, const Params& P, int s, int head, int qb, float sref) {
;     ...
;         const unsigned dvoff = (unsigned)(wid * 1024 + lane * 16);
;         const unsigned kdst = lds0 + L_K + wid * 1024, vdst = lds0 + L_V + wid * 1024;
;     ...
;         __syncthreads();
;         DMA(0, 0); DMA(1, 1); DMA(2, 2);
;         bf16x8 qr[4];
; #pragma unroll
;         for (int d0 = 0; d0 < 4; ++d0) qr[d0] = *(const bf16x8*)(Qw + (size_t)r32 * 64 + d0 * 16 + hi * 8);
;         constexpr bool ZREF = STAT && !DIFF;
;         float m_reg = (STAT && !ZREF) ? sref : 0.f, l_reg = 0.f, cb = 0.f; bool moved = true;
;         if constexpr (STAT && DIFF) {
;             float q2 = 0.f;
; #pragma unroll
;             for (int d0 = 0; d0 < 4; ++d0)
; #pragma unroll
;                 for (int i = 0; i < 8; ++i) { const float f = __builtin_bit_cast(float, (unsigned)(unsigned short)qr[d0][i] << 16); q2 += f * f; }
;             { auto rr = __builtin_amdgcn_permlane32_swap(__float_as_uint(q2), __float_as_uint(q2), false, false); q2 = __uint_as_float(rr[0]) + __uint_as_float(rr[1]); }
;             const float kn2 = __uint_as_float(((const unsigned*)(ws + WS_BAR))[3800 + s * 8 + head * 2 + mp]);
;             m_reg = __builtin_sqrtf(q2 * kn2) * 1.001f + 0.01f + sref;
;         }
;         f32x16 negm;
; #pragma unroll
;         for (int d = 0; d < NCB; ++d) o[d] = f32x16{};
;         f32x16 pA0, pA1, pB0, pB1; float alA = 1.f, alB = 1.f;
;         u32x4 pw[4];
;         int bm = 0, ix = 0;
;         WAIT_BAR();
;         BMODE(0); NEGM();
;         { const LAS char* kp_ = kp0;
; #pragma unroll
;           for (int d0 = 0; d0 < 4; ++d0) { const bf16x8 b0 = *(const LAS bf16x8*)(kp_ + d0 * 2048), b1 = *(const LAS bf16x8*)(kp_ + d0 * 2048 + 512);
;               if (d0 == 0) { if constexpr (ZREF) { pA0 = MFMA32(b0, qr[0], f32x16{}); pA1 = MFMA32(b1, qr[0], f32x16{}); } else { pA0 = MFMA32(b0, qr[0], negm); pA1 = MFMA32(b1, qr[0], negm); } } else { pA0 = MFMA32(b0, qr[d0], pA0); pA1 = MFMA32(b1, qr[d0], pA1); } } }
.LBB0_588:
	v_readlane_b32 s4, v254, 45
	v_readlane_b32 s5, v254, 46
	s_lshl_b32 s8, s64, 14
	s_nop 3
	global_load_dword v1, v0, s[4:5]
	s_lshl_b32 s4, s64, 12
	s_add_i32 s9, s4, 0x6000
	s_cmp_lt_u32 s64, 2
	s_cselect_b64 s[4:5], -1, 0
	s_and_b64 s[6:7], s[4:5], exec
	s_mov_b32 s6, 0x42200000
	s_cselect_b32 s48, 0x100, 64
	s_cselect_b32 s14, s8, s9
	s_lshl_b32 s42, s63, 8
	s_waitcnt vmcnt(0)
	v_cmp_nge_f32_e32 vcc, s6, v1
	s_cbranch_vccnz .LBB0_595
	v_mov_b32_e32 v42, v230
	s_lshl_b64 s[6:7], s[14:15], 3
	v_readfirstlane_b32 s9, v42
	s_ashr_i32 s8, s9, 6
	s_lshl_b32 s43, s8, 5
	s_add_i32 s43, s43, s42
	s_and_b64 s[12:13], s[4:5], exec
	s_mov_b32 s73, s15
	s_cselect_b32 s40, 14, 12
	s_lshl_b64 s[12:13], s[72:73], s40
	s_add_u32 s6, s6, s12
	s_addc_u32 s7, s7, s13
	s_ashr_i32 s12, s43, 31
	s_add_u32 s6, s6, s43
	s_addc_u32 s7, s7, s12
	s_lshl_b64 s[6:7], s[6:7], 7
	s_add_u32 s12, s92, s6
	s_addc_u32 s13, s93, s7
	s_lshr_b32 s6, s72, 2
	s_mov_b32 s7, s15
	s_lshl_b64 s[6:7], s[6:7], s40
	s_lshl_b64 s[40:41], s[14:15], 8
	s_lshl_b64 s[6:7], s[6:7], 7
	s_add_u32 s6, s40, s6
	s_addc_u32 s7, s41, s7
	v_readlane_b32 s16, v254, 47
	s_add_u32 s40, s16, s6
	v_readlane_b32 s16, v254, 48
	s_addc_u32 s41, s16, s7
	v_readlane_b32 s16, v254, 49
	v_and_b32_e32 v133, 63, v42
	s_add_u32 s6, s16, s6
	v_readlane_b32 s16, v254, 50
	v_lshlrev_b32_e32 v43, 4, v133
	s_addc_u32 s7, s16, s7
	s_lshl_b32 s47, s8, 10
	v_or_b32_e32 v134, s47, v43
	s_add_i32 s46, s47, s65
	s_add_i32 s47, s47, 0
	s_add_u32 s50, s40, 0x2000
	s_addc_u32 s51, s41, 0
	s_add_u32 s54, s6, 0x2000
	s_addc_u32 s55, s7, 0
	s_add_u32 s56, s40, 0x4000
	v_and_b32_e32 v132, 31, v42
	s_addc_u32 s57, s41, 0
	s_barrier
	s_mov_b32 s8, m0
	s_mov_b32 m0, s46
	s_nop 0
	global_load_lds_dwordx4 v134, s[40:41]
	s_mov_b32 m0, s8
	s_add_u32 s58, s6, 0x4000
	v_lshlrev_b32_e32 v2, 7, v132
	v_mov_b32_e32 v3, v0
	s_mov_b32 s8, m0
	s_mov_b32 m0, s47
	s_nop 0
	global_load_lds_dwordx4 v134, s[6:7]
	s_mov_b32 m0, s8
	s_addc_u32 s59, s7, 0
	v_lshl_add_u64 v[2:3], s[12:13], 0, v[2:3]
	s_add_i32 s8, s47, 0x16000
	s_mov_b32 s12, m0
	s_mov_b32 m0, s8
	s_nop 0
	global_load_lds_dwordx4 v134, s[50:51]
	s_mov_b32 m0, s12
	v_bfe_u32 v150, v42, 5, 1
	s_add_i32 s8, s47, 0x4000
	s_mov_b32 s12, m0
	s_mov_b32 m0, s8
	s_nop 0
	global_load_lds_dwordx4 v134, s[54:55]
	s_mov_b32 m0, s12
	v_lshlrev_b32_e32 v148, 4, v150
	v_mov_b32_e32 v149, v0
	s_add_i32 s8, s47, 0x18000
	s_mov_b32 s12, m0
	s_mov_b32 m0, s8
	s_nop 0
	global_load_lds_dwordx4 v134, s[56:57]
	s_mov_b32 m0, s12
	v_lshl_add_u64 v[6:7], v[2:3], 0, v[148:149]
	s_add_i32 s8, s47, 0x8000
	s_mov_b32 s12, m0
	s_mov_b32 m0, s8
	s_nop 0
	global_load_lds_dwordx4 v134, s[58:59]
	s_mov_b32 m0, s12
	global_load_dwordx4 v[124:127], v[6:7], off
	global_load_dwordx4 v[120:123], v[6:7], off offset:32
	global_load_dwordx4 v[116:119], v[6:7], off offset:64
	global_load_dwordx4 v[112:115], v[6:7], off offset:96
	v_mov_b32_e32 v2, v0
	v_mov_b32_e32 v3, v0
	v_mov_b32_e32 v4, v0
	v_mov_b32_e32 v5, v0
	v_mov_b32_e32 v6, v0
	v_mov_b32_e32 v7, v0
	v_mov_b32_e32 v8, v0
	v_mov_b32_e32 v9, v0
	v_mov_b32_e32 v10, v0
	v_mov_b32_e32 v11, v0
	v_mov_b32_e32 v12, v0
	v_mov_b32_e32 v13, v0
	v_mov_b32_e32 v14, v0
	v_mov_b32_e32 v15, v0
	v_mov_b32_e32 v1, v0
	v_mov_b64_e32 v[16:17], v[14:15]
	v_mov_b64_e32 v[14:15], v[12:13]
	v_mov_b64_e32 v[12:13], v[10:11]
	v_mov_b64_e32 v[10:11], v[8:9]
	v_mov_b64_e32 v[8:9], v[6:7]
	v_mov_b64_e32 v[6:7], v[4:5]
	v_mov_b64_e32 v[4:5], v[2:3]
	v_mov_b64_e32 v[2:3], v[0:1]
	v_lshlrev_b32_e32 v1, 10, v150
	v_lshlrev_b32_e32 v18, 4, v132
	v_add3_u32 v135, s65, v1, v18
	s_waitcnt vmcnt(0) lgkmcnt(0)
	s_barrier
	ds_read_b128 v[2:5], v135
	ds_read_b128 v[18:21], v135 offset:512
	ds_read_b128 v[34:37], v135 offset:2048
	ds_read_b128 v[38:41], v135 offset:2560
	s_add_i32 s50, s48, -1
	v_lshlrev_b32_e32 v1, 1, v42
	v_lshlrev_b32_e32 v42, 3, v133
	s_add_u32 s6, s6, 0x8000
	s_addc_u32 s7, s7, 0
	v_and_b32_e32 v1, 32, v1
	s_add_u32 s40, s40, 0x8000
	s_mov_b32 s49, 4
	s_mov_b32 s8, 1
	s_mov_b32 s54, 0
	s_addc_u32 s41, s41, 0
	s_waitcnt vmcnt(3) lgkmcnt(3)
	v_mfma_f32_32x32x16_bf16 v[2:17], v[2:5], v[124:127], 0
	s_waitcnt lgkmcnt(2)
	v_mfma_f32_32x32x16_bf16 v[18:33], v[18:21], v[124:127], 0
	s_waitcnt vmcnt(2) lgkmcnt(1)
	v_mfma_f32_32x32x16_bf16 v[2:17], v[34:37], v[120:123], v[2:17]
	s_waitcnt lgkmcnt(0)
	v_mfma_f32_32x32x16_bf16 v[18:33], v[38:41], v[120:123], v[18:33]
	ds_read_b128 v[34:37], v135 offset:4096
	ds_read_b128 v[38:41], v135 offset:4608
	s_waitcnt vmcnt(1) lgkmcnt(1)
	v_mfma_f32_32x32x16_bf16 v[2:17], v[34:37], v[116:119], v[2:17]
	ds_read_b128 v[34:37], v135 offset:6144
	s_waitcnt lgkmcnt(1)
	v_mfma_f32_32x32x16_bf16 v[18:33], v[38:41], v[116:119], v[18:33]
	ds_read_b128 v[38:41], v135 offset:6656
	s_waitcnt vmcnt(0) lgkmcnt(1)
	v_mfma_f32_32x32x16_bf16 v[2:17], v[34:37], v[112:115], v[2:17]
	v_and_b32_e32 v34, 24, v42
	v_and_b32_e32 v35, 0xc0, v43
	v_and_b32_e32 v36, 0x100, v42
	v_add3_u32 v34, 0, v34, v35
	v_add3_u32 v1, v34, v1, v36
	s_nop 6
	v_exp_f32_e32 v64, v2
	s_waitcnt lgkmcnt(0)
; template <int NCB, bool DIFF, bool STAT>
; __device__ __forceinline__ void attn_unit(LAS char* lds, const Params& P, int s, int head, int qb, float sref) {
;     ...
;         if constexpr (!STAT) rowmax_decide<DIFF, true>(pA0, pA1, m_reg, alA, moved, bm, tab, ix); else moved = false;
; #pragma unroll
;         for (int r = 0; r < 16; ++r) { pA0[r] = __builtin_amdgcn_exp2f(pA0[r]); pA1[r] = __builtin_amdgcn_exp2f(pA1[r]); }
;         int sl_prev = 0, sl_cur = 1;
;         bf16x8 kf[3];
	v_mfma_f32_32x32x16_bf16 v[18:33], v[38:41], v[112:115], v[18:33]
	v_exp_f32_e32 v65, v3
	v_exp_f32_e32 v66, v4
	v_exp_f32_e32 v67, v5
	v_exp_f32_e32 v68, v6
	v_exp_f32_e32 v69, v7
	v_exp_f32_e32 v70, v8
	v_exp_f32_e32 v71, v9
	s_nop 4
	v_exp_f32_e32 v48, v18
	v_exp_f32_e32 v49, v19
	v_exp_f32_e32 v50, v20
	v_exp_f32_e32 v51, v21
	v_exp_f32_e32 v52, v22
	v_exp_f32_e32 v53, v23
	v_exp_f32_e32 v54, v24
	v_exp_f32_e32 v55, v25
	v_exp_f32_e32 v56, v26
	v_exp_f32_e32 v57, v27
	v_exp_f32_e32 v58, v28
	v_exp_f32_e32 v59, v29
	v_exp_f32_e32 v60, v30
	v_exp_f32_e32 v61, v31
	v_exp_f32_e32 v62, v32
	v_exp_f32_e32 v63, v33
	v_exp_f32_e32 v72, v10
	v_exp_f32_e32 v73, v11
	v_exp_f32_e32 v74, v12
	v_exp_f32_e32 v75, v13
	v_exp_f32_e32 v76, v14
	v_exp_f32_e32 v77, v15
	v_exp_f32_e32 v78, v16
	v_exp_f32_e32 v79, v17
	v_mov_b32_e32 v14, 0
	v_mov_b32_e32 v144, 0
	v_mov_b32_e32 v145, 0
	v_mov_b32_e32 v146, 0
	v_mov_b32_e32 v147, 0
	v_and_b32_e32 v140, 15, v230
	v_bfe_u32 v141, v230, 4, 1
	v_mov_b32_e32 v142, 0x3f803f80
	v_cmp_eq_u32_e64 s[98:99], v140, v141
	s_nop 1
	v_cndmask_b32_e64 v140, 0, v142, s[98:99]
	v_mov_b32_e32 v141, v140
	v_mov_b32_e32 v142, v140
	v_mov_b32_e32 v143, v140
	v_mov_b32_e32 v16, 0
	v_mov_b32_e32 v17, v14
	v_mov_b32_e32 v18, v14
	v_mov_b32_e32 v19, v14
	v_mov_b32_e32 v20, v14
	v_mov_b32_e32 v21, v14
	v_mov_b32_e32 v22, v14
	v_mov_b32_e32 v23, v14
	v_mov_b32_e32 v24, v14
	v_mov_b32_e32 v25, v14
	v_mov_b32_e32 v26, v14
	v_mov_b32_e32 v27, v14
	v_mov_b32_e32 v28, v14
	v_mov_b32_e32 v29, v14
	v_mov_b32_e32 v30, v14
	v_mov_b32_e32 v31, v14
	v_mov_b32_e32 v32, 0
	v_mov_b32_e32 v33, v14
	v_mov_b32_e32 v34, v14
	v_mov_b32_e32 v35, v14
	v_mov_b32_e32 v36, v14
	v_mov_b32_e32 v37, v14
	v_mov_b32_e32 v38, v14
	v_mov_b32_e32 v39, v14
	v_mov_b32_e32 v40, v14
	v_mov_b32_e32 v41, v14
	v_mov_b32_e32 v42, v14
	v_mov_b32_e32 v43, v14
	v_mov_b32_e32 v44, v14
	v_mov_b32_e32 v45, v14
	v_mov_b32_e32 v46, v14
	v_mov_b32_e32 v47, v14
	s_lshl_b32 s12, s54, 14
	v_lshl_add_u32 v136, s8, 13, v135
	v_add_u32_e32 v15, s12, v1
	ds_read_b128 v[2:5], v136
	ds_read_b128 v[6:9], v136 offset:512
	s_branch .Lqka_after_reads
.LBB0_590:
	s_waitcnt lgkmcnt(2)
	v_mfma_f32_32x32x16_bf16 v[16:31], v[128:131], v[48:51], v[16:31]
	ds_read_b64_tr_b16 v[56:57], v15 offset:2048
	ds_read_b64_tr_b16 v[58:59], v15 offset:3072
	v_mfma_f32_16x16x32_bf16 v[144:147], v[2:5], v[140:143], v[144:147]
	v_exp_f32_e32 v96, v96
	v_exp_f32_e32 v97, v97
	v_exp_f32_e32 v98, v98
	v_exp_f32_e32 v99, v99
	s_waitcnt lgkmcnt(2)
	v_mfma_f32_32x32x16_bf16 v[32:47], v[128:131], v[52:55], v[32:47]
	ds_read_b64_tr_b16 v[48:49], v15 offset:2560
	ds_read_b64_tr_b16 v[50:51], v15 offset:3584
	v_exp_f32_e32 v100, v100
	v_exp_f32_e32 v101, v101
	v_exp_f32_e32 v102, v102
	v_exp_f32_e32 v103, v103
	s_waitcnt lgkmcnt(2)
	v_mfma_f32_32x32x16_bf16 v[16:31], v[10:13], v[56:59], v[16:31]
	ds_read_b64_tr_b16 v[52:53], v15 offset:4096
	ds_read_b64_tr_b16 v[54:55], v15 offset:5120
	v_exp_f32_e32 v104, v104
	v_exp_f32_e32 v105, v105
	v_exp_f32_e32 v106, v106
	v_exp_f32_e32 v107, v107
	s_waitcnt lgkmcnt(2)
	v_mfma_f32_32x32x16_bf16 v[32:47], v[10:13], v[48:51], v[32:47]
	ds_read_b64_tr_b16 v[56:57], v15 offset:4608
	ds_read_b64_tr_b16 v[58:59], v15 offset:5632
	v_exp_f32_e32 v108, v108
	v_exp_f32_e32 v109, v109
	v_exp_f32_e32 v110, v110
	v_exp_f32_e32 v111, v111
	s_waitcnt lgkmcnt(2)
	v_mfma_f32_32x32x16_bf16 v[16:31], v[6:9], v[52:55], v[16:31]
	ds_read_b64_tr_b16 v[10:11], v15 offset:6144
	ds_read_b64_tr_b16 v[12:13], v15 offset:7168
	v_exp_f32_e32 v80, v80
	v_exp_f32_e32 v81, v81
	v_exp_f32_e32 v82, v82
	v_exp_f32_e32 v83, v83
	s_waitcnt lgkmcnt(2)
	v_mfma_f32_32x32x16_bf16 v[32:47], v[6:9], v[56:59], v[32:47]
	ds_read_b64_tr_b16 v[48:49], v15 offset:6656
	ds_read_b64_tr_b16 v[50:51], v15 offset:7680
	v_exp_f32_e32 v84, v84
	v_exp_f32_e32 v85, v85
	v_exp_f32_e32 v86, v86
	v_exp_f32_e32 v87, v87
	s_waitcnt lgkmcnt(2)
	v_mfma_f32_32x32x16_bf16 v[16:31], v[2:5], v[10:13], v[16:31]
	v_exp_f32_e32 v88, v88
	v_exp_f32_e32 v89, v89
	v_exp_f32_e32 v90, v90
	v_exp_f32_e32 v91, v91
	s_waitcnt lgkmcnt(0)
	v_mfma_f32_32x32x16_bf16 v[32:47], v[2:5], v[48:51], v[32:47]
	v_exp_f32_e32 v92, v92
	v_exp_f32_e32 v93, v93
	v_exp_f32_e32 v94, v94
	v_exp_f32_e32 v95, v95
	s_add_i32 s12, s8, -4
	s_add_i32 s13, s8, 1
	s_cmp_gt_i32 s8, 3
	s_cselect_b32 s12, s12, s13
	v_lshl_add_u32 v6, s12, 13, v135
	ds_read_b128 v[2:5], v6
	ds_read_b128 v[6:9], v6 offset:512
	s_cmp_lg_u32 s8, 4
	s_cselect_b32 s54, s13, 0
	v_lshl_add_u32 v15, s54, 13, v135
	v_lshl_add_u32 v128, s8, 14, v1
	s_waitcnt lgkmcnt(1)
	v_mfma_f32_32x32x16_bf16 v[64:79], v[2:5], v[124:127], 0
	ds_read_b128 v[10:13], v15 offset:2048
	v_cvt_pk_bf16_f32 v2, v96, v97
	v_cvt_pk_bf16_f32 v3, v98, v99
	s_nop 0
	ds_read_b128 v[96:99], v15 offset:2560
	v_cvt_pk_bf16_f32 v4, v100, v101
	s_waitcnt lgkmcnt(2)
	v_mfma_f32_32x32x16_bf16 v[48:63], v[6:9], v[124:127], 0
	v_cvt_pk_bf16_f32 v5, v102, v103
	s_waitcnt lgkmcnt(1)
	v_mfma_f32_32x32x16_bf16 v[64:79], v[10:13], v[120:123], v[64:79]
	ds_read_b128 v[6:9], v15 offset:4096
	v_mfma_f32_16x16x32_bf16 v[144:147], v[2:5], v[140:143], v[144:147]
	v_cvt_pk_bf16_f32 v10, v104, v105
	v_cvt_pk_bf16_f32 v11, v106, v107
	s_waitcnt lgkmcnt(1)
	v_mfma_f32_32x32x16_bf16 v[48:63], v[96:99], v[120:123], v[48:63]
	ds_read_b128 v[100:103], v15 offset:4608
	v_cvt_pk_bf16_f32 v12, v108, v109
	v_cvt_pk_bf16_f32 v13, v110, v111
	s_waitcnt lgkmcnt(1)
	v_mfma_f32_32x32x16_bf16 v[64:79], v[6:9], v[116:119], v[64:79]
	ds_read_b128 v[96:99], v15 offset:6144
	v_mfma_f32_16x16x32_bf16 v[144:147], v[10:13], v[140:143], v[144:147]
	v_cvt_pk_bf16_f32 v6, v80, v81
	v_cvt_pk_bf16_f32 v7, v82, v83
	s_waitcnt lgkmcnt(1)
	v_mfma_f32_32x32x16_bf16 v[48:63], v[100:103], v[116:119], v[48:63]
	ds_read_b128 v[80:83], v15 offset:6656
	v_cvt_pk_bf16_f32 v8, v84, v85
	v_cvt_pk_bf16_f32 v9, v86, v87
	s_waitcnt lgkmcnt(1)
	v_mfma_f32_32x32x16_bf16 v[64:79], v[96:99], v[112:115], v[64:79]
	v_cvt_pk_bf16_f32 v84, v88, v89
	v_cvt_pk_bf16_f32 v85, v90, v91
	v_mfma_f32_16x16x32_bf16 v[144:147], v[6:9], v[140:143], v[144:147]
	ds_read_b64_tr_b16 v[88:89], v128
	ds_read_b64_tr_b16 v[90:91], v128 offset:1024
	s_waitcnt lgkmcnt(2)
	v_mfma_f32_32x32x16_bf16 v[48:63], v[80:83], v[112:115], v[48:63]
	v_cvt_pk_bf16_f32 v86, v92, v93
	v_cvt_pk_bf16_f32 v87, v94, v95
	ds_read_b64_tr_b16 v[80:81], v128 offset:512
	ds_read_b64_tr_b16 v[82:83], v128 offset:1536
	s_waitcnt lgkmcnt(2)
	v_mfma_f32_32x32x16_bf16 v[16:31], v[2:5], v[88:91], v[16:31]
	ds_read_b64_tr_b16 v[92:93], v128 offset:2048
	ds_read_b64_tr_b16 v[94:95], v128 offset:3072
	v_mfma_f32_16x16x32_bf16 v[144:147], v[84:87], v[140:143], v[144:147]
	v_exp_f32_e32 v64, v64
	v_exp_f32_e32 v65, v65
	v_exp_f32_e32 v66, v66
	v_exp_f32_e32 v67, v67
	s_waitcnt lgkmcnt(2)
	v_mfma_f32_32x32x16_bf16 v[32:47], v[2:5], v[80:83], v[32:47]
	ds_read_b64_tr_b16 v[88:89], v128 offset:2560
	ds_read_b64_tr_b16 v[90:91], v128 offset:3584
	v_exp_f32_e32 v68, v68
	v_exp_f32_e32 v69, v69
	v_exp_f32_e32 v70, v70
	v_exp_f32_e32 v71, v71
	s_waitcnt lgkmcnt(2)
	v_mfma_f32_32x32x16_bf16 v[16:31], v[10:13], v[92:95], v[16:31]
	ds_read_b64_tr_b16 v[2:3], v128 offset:4096
	ds_read_b64_tr_b16 v[4:5], v128 offset:5120
	v_exp_f32_e32 v72, v72
	v_exp_f32_e32 v73, v73
	v_exp_f32_e32 v74, v74
	v_exp_f32_e32 v75, v75
	s_waitcnt lgkmcnt(2)
	v_mfma_f32_32x32x16_bf16 v[32:47], v[10:13], v[88:91], v[32:47]
	ds_read_b64_tr_b16 v[80:81], v128 offset:4608
	ds_read_b64_tr_b16 v[82:83], v128 offset:5632
	v_exp_f32_e32 v76, v76
	v_exp_f32_e32 v77, v77
	v_exp_f32_e32 v78, v78
	v_exp_f32_e32 v79, v79
	s_waitcnt lgkmcnt(2)
	v_mfma_f32_32x32x16_bf16 v[16:31], v[6:9], v[2:5], v[16:31]
	ds_read_b64_tr_b16 v[10:11], v128 offset:6144
	ds_read_b64_tr_b16 v[12:13], v128 offset:7168
	v_exp_f32_e32 v48, v48
	v_exp_f32_e32 v49, v49
	v_exp_f32_e32 v50, v50
	v_exp_f32_e32 v51, v51
	s_waitcnt lgkmcnt(2)
	v_mfma_f32_32x32x16_bf16 v[32:47], v[6:9], v[80:83], v[32:47]
	ds_read_b64_tr_b16 v[2:3], v128 offset:6656
	ds_read_b64_tr_b16 v[4:5], v128 offset:7680
	v_exp_f32_e32 v52, v52
	v_exp_f32_e32 v53, v53
	v_exp_f32_e32 v54, v54
	v_exp_f32_e32 v55, v55
	s_waitcnt lgkmcnt(2)
	v_mfma_f32_32x32x16_bf16 v[16:31], v[84:87], v[10:13], v[16:31]
	v_exp_f32_e32 v56, v56
	v_exp_f32_e32 v57, v57
	v_exp_f32_e32 v58, v58
	v_exp_f32_e32 v59, v59
	s_waitcnt lgkmcnt(0)
	v_mfma_f32_32x32x16_bf16 v[32:47], v[84:87], v[2:5], v[32:47]
	v_exp_f32_e32 v60, v60
	v_exp_f32_e32 v61, v61
	v_exp_f32_e32 v62, v62
	v_exp_f32_e32 v63, v63
	s_add_i32 s8, s54, 1
	s_cmp_lg_u32 s54, 4
	s_cselect_b32 s8, s8, 0
	v_lshl_add_u32 v136, s8, 13, v135
	s_cmp_lt_u32 s51, s50
	s_waitcnt vmcnt(0) lgkmcnt(0)
	s_barrier
	s_cbranch_scc0 .LBB0_596
.LBB0_591:
	ds_read_b128 v[2:5], v136
	ds_read_b128 v[6:9], v136 offset:512
	s_add_u32 s6, s6, 0x4000
	s_addc_u32 s7, s7, 0
	s_add_u32 s40, s40, 0x4000
	s_addc_u32 s41, s41, 0
	s_add_i32 s49, s49, 2
	s_lshl_b32 s12, s54, 14
	v_add_u32_e32 v15, s12, v1
.Lqka_after_reads:
	s_waitcnt lgkmcnt(1)
	v_mfma_f32_32x32x16_bf16 v[96:111], v[2:5], v[124:127], 0
	ds_read_b128 v[10:13], v136 offset:2048
	v_cvt_pk_bf16_f32 v128, v64, v65
	v_cvt_pk_bf16_f32 v129, v66, v67
	s_waitcnt lgkmcnt(1)
	v_mfma_f32_32x32x16_bf16 v[80:95], v[6:9], v[124:127], 0
	ds_read_b128 v[2:5], v136 offset:2560
	v_cvt_pk_bf16_f32 v130, v68, v69
	v_cvt_pk_bf16_f32 v131, v70, v71
	s_waitcnt lgkmcnt(1)
	v_mfma_f32_32x32x16_bf16 v[96:111], v[10:13], v[120:123], v[96:111]
	ds_read_b128 v[6:9], v136 offset:4096
	v_mfma_f32_16x16x32_bf16 v[144:147], v[128:131], v[140:143], v[144:147]
	v_cvt_pk_bf16_f32 v10, v72, v73
	v_cvt_pk_bf16_f32 v11, v74, v75
	s_waitcnt lgkmcnt(1)
	v_mfma_f32_32x32x16_bf16 v[80:95], v[2:5], v[120:123], v[80:95]
	ds_read_b128 v[64:67], v136 offset:4608
	v_cvt_pk_bf16_f32 v12, v76, v77
	v_cvt_pk_bf16_f32 v13, v78, v79
	s_waitcnt lgkmcnt(1)
	v_mfma_f32_32x32x16_bf16 v[96:111], v[6:9], v[116:119], v[96:111]
	ds_read_b128 v[2:5], v136 offset:6144
	v_mfma_f32_16x16x32_bf16 v[144:147], v[10:13], v[140:143], v[144:147]
	v_cvt_pk_bf16_f32 v6, v48, v49
	v_cvt_pk_bf16_f32 v7, v50, v51
	s_waitcnt lgkmcnt(1)
	v_mfma_f32_32x32x16_bf16 v[80:95], v[64:67], v[116:119], v[80:95]
	ds_read_b128 v[68:71], v136 offset:6656
	v_cvt_pk_bf16_f32 v8, v52, v53
	v_cvt_pk_bf16_f32 v9, v54, v55
	s_waitcnt lgkmcnt(1)
	v_mfma_f32_32x32x16_bf16 v[96:111], v[2:5], v[112:115], v[96:111]
	v_cvt_pk_bf16_f32 v2, v56, v57
	v_cvt_pk_bf16_f32 v3, v58, v59
	v_mfma_f32_16x16x32_bf16 v[144:147], v[6:9], v[140:143], v[144:147]
	ds_read_b64_tr_b16 v[48:49], v15
	ds_read_b64_tr_b16 v[50:51], v15 offset:1024
	s_waitcnt lgkmcnt(2)
	v_mfma_f32_32x32x16_bf16 v[80:95], v[68:71], v[112:115], v[80:95]
	v_cvt_pk_bf16_f32 v4, v60, v61
	v_cvt_pk_bf16_f32 v5, v62, v63
	ds_read_b64_tr_b16 v[52:53], v15 offset:512
	ds_read_b64_tr_b16 v[54:55], v15 offset:1536
	s_add_i32 s51, s49, -1
	s_cmp_ge_u32 s51, s48
	s_cbranch_scc1 .LBB0_593
	s_add_u32 s12, s40, 0xffffe000
	s_addc_u32 s13, s41, -1
	s_cmp_gt_i32 s8, 2
	s_cselect_b32 s54, -3, 2
	s_add_i32 s54, s54, s8
	s_lshl_b32 s55, s54, 13
	s_add_i32 s55, s55, s46
	s_mov_b32 m0, s55
	s_nop 0
	global_load_lds_dwordx4 v134, s[12:13]
	s_add_u32 s12, s6, 0xffffe000
	s_addc_u32 s13, s7, -1
	s_lshl_b32 s54, s54, 14
	s_add_i32 s54, s54, s47
	s_mov_b32 m0, s54
	s_nop 0
	global_load_lds_dwordx4 v134, s[12:13]
